# k20 plus: static s_setprio 1 for waves 4-7 across the dilated-attention phase (cleared at the phase exit)
# baseline (speedup 1.0000x reference)
; #define LAS __attribute__((address_space(3)))
; __device__ __forceinline__ void attn_dil_phase(LAS unsigned char* lds, const bf16_t* QKV, const float* BT, bf16_t* OG, float* LSE, int nseq, int log2S, int G, int bx) {
;     constexpr int KBUF = 64 * 272, VBUF = 16384, VOFF = 2 * KBUF, TOFF = VOFF + 2 * VBUF;
;     int tid_ = threadIdx.x; asm volatile("" : "+v"(tid_));
;     const int tid = tid_, wid = __builtin_amdgcn_readfirstlane(tid >> 6), lane = tid & 63, r32 = lane & 31, hi = lane >> 5;
;     const int S = 1 << log2S, nqb = S >> 8, nunits = nseq * 24 * nqb;
;     const int key0 = tid >> 4, ch0 = tid & 15;
.LBB0_279:
.LBB0_280:
	v_readfirstlane_b32 vcc_lo, v216
	s_nop 3
	s_lshr_b32 vcc_lo, vcc_lo, 8
	s_cmp_eq_u32 vcc_lo, 0
	s_cbranch_scc1 .Ldil_prio_skip
	s_setprio 1

; #define PH_WS const __attribute__((address_space(4))) Params* kp = (const __attribute__((address_space(4))) Params*)__builtin_amdgcn_kernarg_segment_ptr(); asm volatile("" : "+s"(kp)); \
;         unsigned char* ws = kp->ws; float* X = kp->out; (void)X; int G = G0, bx = bx0; asm volatile("" : "+s"(G), "+s"(bx)); const int NGW = G * 8; (void)NGW
; #define REP(k) for (int rep_ = 0; rep_ < ((((MK_REP) >> (k)) & 1u) ? 2 : 1); ++rep_)
; #define PH_END do { if (ph >= lo && ph + 1 < hi) { if (lo < 0) grid.sync(); else xcd_barrier(xbar); } ++ph; } while (0)
; __global__ void __launch_bounds__(512, 2) mega_fwd(Params p) {
;     ...
;             PH_END;
;             if (EN(2) && PH_ON) REP(2) { PH_WS; attn_dil_phase(lds, QKV, BT, OG, LSE, nseq, log2S, G, bx); }
;             PH_END;
;             if (EN(3) && PH_ON) REP(3) {   PH_LOCALS;
;                 for (int r = gw; r < CHUNK; r += NGW) {
;                     const int h = lane >> 3;
;                     const float l0 = LSE[((size_t)0 * CHUNK + r) * 8 + h], l1 = LSE[((size_t)1 * CHUNK + r) * 8 + h], l2 = LSE[((size_t)2 * CHUNK + r) * 8 + h];
.LBB0_372:
.LBB0_373:
	s_setprio 0
	s_cmp_ge_i32 s0, s70
	s_cselect_b64 s[6:7], -1, 0
	s_and_b64 s[0:1], s[6:7], s[18:19]
	s_andn2_b64 vcc, exec, s[0:1]
	s_cbranch_vccnz .LBB0_377
	s_mov_b64 s[18:19], s[64:65]
	s_mov_b32 s0, s66
	v_readlane_b32 s8, v254, 0
	v_mov_b32_e32 v2, v216
	s_lshl_b32 s2, s0, 3
	v_readfirstlane_b32 s1, v2
	s_ashr_i32 s1, s1, 6
	s_add_i32 s0, s1, s2
	s_cmpk_gt_i32 s0, 0x3fff
	v_readlane_b32 s9, v254, 1
	s_cbranch_scc1 .LBB0_377
	s_load_dwordx2 s[18:19], s[18:19], 0x90
	v_lshlrev_b32_e32 v0, 5, v2
	v_and_b32_e32 v0, 0x7e0, v0
	s_lshl_b32 s20, s8, 3
	s_mov_b64 s[8:9], 0xde00000
	s_waitcnt lgkmcnt(0)
	v_lshl_add_u64 v[4:5], s[18:19], 0, v[0:1]
	s_ashr_i32 s10, s1, 31
	v_lshl_add_u64 v[10:11], v[4:5], 0, s[8:9]
	s_ashr_i32 s9, s2, 31
	s_add_u32 s8, s1, s2
	s_addc_u32 s9, s10, s9
	s_lshl_b64 s[14:15], s[8:9], 11
	v_or_b32_e32 v12, s14, v0
	s_ashr_i32 s21, s20, 31
	s_lshl_b64 s[8:9], s[8:9], 5
	v_lshrrev_b32_e32 v0, 1, v2
	v_mov_b32_e32 v13, s15
	s_lshl_b64 s[22:23], s[20:21], 11
	v_and_or_b32 v14, v0, 28, s8
	v_mov_b32_e32 v15, s9
	s_lshl_b64 s[24:25], s[20:21], 5
